# EpiUp: fused 24 dpp-mov + cndmask(fr!=0) pairs into single dpp movs (bound_ctrl zero-fills row lane 0)
# speedup vs baseline: 1.0032x; 1.0032x over previous
.LBB0_402:
	s_or_b64 exec, exec, s[38:39]
	v_mov_b32_dpp v169, v133 row_shr:1 row_mask:0xf bank_mask:0xf bound_ctrl:1
	v_mov_b32_dpp v168, v132 row_shr:1 row_mask:0xf bank_mask:0xf bound_ctrl:1
	v_mov_b32_dpp v167, v131 row_shr:1 row_mask:0xf bank_mask:0xf bound_ctrl:1
	v_mov_b32_dpp v166, v130 row_shr:1 row_mask:0xf bank_mask:0xf bound_ctrl:1
	v_mov_b32_dpp v173, v105 row_shr:1 row_mask:0xf bank_mask:0xf bound_ctrl:1
	v_mov_b32_dpp v172, v104 row_shr:1 row_mask:0xf bank_mask:0xf bound_ctrl:1
	v_mov_b32_dpp v171, v103 row_shr:1 row_mask:0xf bank_mask:0xf bound_ctrl:1
	v_mov_b32_dpp v170, v102 row_shr:1 row_mask:0xf bank_mask:0xf bound_ctrl:1
	s_and_saveexec_b64 s[38:39], s[26:27]
	s_cbranch_execz .LBB0_404
	ds_read_b128 v[170:173], v233 offset:32
	ds_read_b128 v[166:169], v233 offset:96
.LBB0_404:
	s_or_b64 exec, exec, s[38:39]
	v_add_co_u32_e32 v78, vcc, 0x5000, v86
	s_nop 0
	v_addc_co_u32_e32 v79, vcc, 0, v87, vcc
	global_load_dwordx4 v[190:193], v[86:87], off offset:16
	global_load_dwordx4 v[194:197], v[78:79], off offset:2064
	v_add_co_u32_e32 v78, vcc, 0xb000, v86
	s_nop 0
	v_addc_co_u32_e32 v79, vcc, 0, v87, vcc
	v_add_co_u32_e32 v80, vcc, 0x2000, v86
	s_nop 0
	v_addc_co_u32_e32 v81, vcc, 0, v87, vcc
	v_add_co_u32_e32 v90, vcc, 0xd000, v86
	global_load_dwordx4 v[198:201], v[78:79], off offset:16
	s_nop 0
	global_load_dwordx4 v[78:81], v[80:81], off offset:3088
	v_addc_co_u32_e32 v91, vcc, 0, v87, vcc
	global_load_dwordx4 v[86:89], v[88:89], off offset:1040
	s_nop 0
	global_load_dwordx4 v[90:93], v[90:91], off offset:3088
	v_mov_b32_dpp v205, v181 row_shr:1 row_mask:0xf bank_mask:0xf bound_ctrl:1
	v_mov_b32_dpp v204, v180 row_shr:1 row_mask:0xf bank_mask:0xf bound_ctrl:1
	v_mov_b32_dpp v203, v179 row_shr:1 row_mask:0xf bank_mask:0xf bound_ctrl:1
	v_mov_b32_dpp v202, v178 row_shr:1 row_mask:0xf bank_mask:0xf bound_ctrl:1
	v_mov_b32_dpp v209, v157 row_shr:1 row_mask:0xf bank_mask:0xf bound_ctrl:1
	v_mov_b32_dpp v208, v156 row_shr:1 row_mask:0xf bank_mask:0xf bound_ctrl:1
	v_mov_b32_dpp v207, v155 row_shr:1 row_mask:0xf bank_mask:0xf bound_ctrl:1
	v_mov_b32_dpp v206, v154 row_shr:1 row_mask:0xf bank_mask:0xf bound_ctrl:1
	s_and_saveexec_b64 s[38:39], s[26:27]
	s_cbranch_execz .LBB0_406
	ds_read_b128 v[206:209], v233 offset:16
	ds_read_b128 v[202:205], v233 offset:80
.LBB0_406:
	s_or_b64 exec, exec, s[38:39]
	v_mov_b32_dpp v97, v77 row_shr:1 row_mask:0xf bank_mask:0xf bound_ctrl:1
	v_mov_b32_dpp v96, v76 row_shr:1 row_mask:0xf bank_mask:0xf bound_ctrl:1
	v_mov_b32_dpp v95, v75 row_shr:1 row_mask:0xf bank_mask:0xf bound_ctrl:1
	v_mov_b32_dpp v94, v74 row_shr:1 row_mask:0xf bank_mask:0xf bound_ctrl:1
	v_mov_b32_dpp v101, v85 row_shr:1 row_mask:0xf bank_mask:0xf bound_ctrl:1
	v_mov_b32_dpp v100, v84 row_shr:1 row_mask:0xf bank_mask:0xf bound_ctrl:1
	v_mov_b32_dpp v99, v83 row_shr:1 row_mask:0xf bank_mask:0xf bound_ctrl:1
	v_mov_b32_dpp v98, v82 row_shr:1 row_mask:0xf bank_mask:0xf bound_ctrl:1
	s_and_saveexec_b64 s[38:39], s[26:27]
	s_cbranch_execz .LBB0_408
	ds_read_b128 v[98:101], v233 offset:48
	ds_read_b128 v[94:97], v233 offset:112
